# gather U and V loops: workgroup barrier at each column-slice boundary keeps the 8 waves on the same L2-resident slice
# speedup vs baseline: 1.0190x; 1.0190x over previous
; #define LAS __attribute__((address_space(3)))
;     ...
;     for (int m = 0; m < 16; m += 2) {
;         const u32x4_t a0 = *(const u32x4_t*)(hp + m * 64), a1 = *(const u32x4_t*)(hp + m * 64 + 64);
; #pragma unroll
;         for (int t = 0; t < NTL; ++t) FP8MM(a0, b0[t], acc[t]);
;         if (m + 2 < 16) {
; #pragma unroll
;             for (int t = 0; t < NTL; ++t) b0[t] = *(const u32x4_t*)(up[t] + (m + 2) * 64);
;         }
; #pragma unroll
;         for (int t = 0; t < NTL; ++t) FP8MM(a1, b1[t], acc[t]);
;         if (m + 3 < 16) {
; #pragma unroll
;             for (int t = 0; t < NTL; ++t) b1[t] = *(const u32x4_t*)(up[t] + (m + 3) * 64);
;         }
;     }
; __global__ void __launch_bounds__(NTHR, 2) mega_fwd(Args a) {
;     ...
;           for (int k0 = 0; gw_ + NGW * k0 < M_P; k0 += 8) {
; #pragma unroll 1
;               for (int k = 0; k < 8; ++k) { const int tok = gw_ + NGW * (k0 + k);
;                   if (tok < M_P) peer_gather_token_t<8, 1>(q_, l_, 0, -1, (LAS float*)nullptr, GARGS, tok, lane_, (LAS unsigned char*)lds + wave * 8192 + k * 1024); }
.Lg1_loop:
	s_and_b32 s9, s22, 7
	s_cmp_lg_u32 s9, 0
	s_cbranch_scc1 .Lg1_nobar
	s_barrier
